# all phase-0 f32->bf16 conversion jobs (cache k/v, cm k/v, sub-keys: 2336 jobs) now run on the phase-1 idle blocks; phase 0 keeps norms, W_in/W_mem transposes, rope
# speedup vs baseline: 1.0312x; 1.0000x over previous
.LBB0_24:
	s_cmpk_lt_i32 s28, 0x35a0
	s_mov_b64 s[8:9], -1
	s_cbranch_scc0 .LBB0_73
	s_cmpk_gt_i32 s28, 0x97f
	s_cbranch_scc0 .LBB0_62
	s_cmpk_gt_u32 s28, 0x359f
	s_cbranch_scc0 .LBB0_23
	s_cmpk_gt_u32 s28, 0x307f
	s_cbranch_scc0 .LBB0_41
	s_cmpk_gt_u32 s28, 0x347f
	s_cbranch_scc0 .LBB0_38
	s_cmpk_gt_u32 s28, 0x34ff
	s_cbranch_scc0 .LBB0_35
	s_cmpk_gt_u32 s28, 0x357f
	s_cbranch_scc0 .LBB0_32
	s_load_dwordx16 s[36:51], s[0:1], 0xc0
	v_add_u32_e32 v65, s60, v69
	v_add_u32_e32 v66, 0xf9500000, v65
	v_mov_b32_e32 v67, v17
	v_add_u32_e32 v104, 0xf9500800, v65
	s_waitcnt lgkmcnt(0)
	v_lshl_add_u64 v[4:5], v[66:67], 2, s[46:47]
	v_mov_b32_e32 v105, v17
	v_add_u32_e32 v106, 0xf9501000, v65
	v_mov_b32_e32 v107, v17
	v_add_u32_e32 v108, 0xf9501800, v65
	v_mov_b32_e32 v109, v17
	global_load_dwordx4 v[0:3], v[4:5], off offset:16
	s_nop 0
	global_load_dwordx4 v[4:7], v[4:5], off
	v_lshl_add_u64 v[12:13], v[104:105], 2, s[46:47]
	v_lshl_add_u64 v[92:93], v[106:107], 2, s[46:47]
	v_lshl_add_u64 v[100:101], v[108:109], 2, s[46:47]
	global_load_dwordx4 v[8:11], v[12:13], off offset:16
	s_nop 0
	global_load_dwordx4 v[12:15], v[12:13], off
	s_nop 0
	global_load_dwordx4 v[88:91], v[92:93], off offset:16
	s_nop 0
	global_load_dwordx4 v[92:95], v[92:93], off
	s_nop 0
	global_load_dwordx4 v[96:99], v[100:101], off
	s_nop 0
	global_load_dwordx4 v[100:103], v[100:101], off offset:16
	v_lshl_add_u64 v[66:67], v[66:67], 1, s[14:15]
	v_lshl_add_u64 v[104:105], v[104:105], 1, s[14:15]
	v_lshl_add_u64 v[106:107], v[106:107], 1, s[14:15]
	v_lshl_add_u64 v[108:109], v[108:109], 1, s[14:15]
	s_mov_b64 s[8:9], 0
	s_waitcnt vmcnt(6)
	v_cvt_pk_bf16_f32 v4, v4, v5
	v_cvt_pk_bf16_f32 v5, v6, v7
	v_cvt_pk_bf16_f32 v6, v0, v1
	v_cvt_pk_bf16_f32 v7, v2, v3
	s_waitcnt vmcnt(4)
	v_cvt_pk_bf16_f32 v0, v12, v13
	v_cvt_pk_bf16_f32 v1, v14, v15
	v_cvt_pk_bf16_f32 v2, v8, v9
	v_cvt_pk_bf16_f32 v3, v10, v11
	s_waitcnt vmcnt(2)
	v_cvt_pk_bf16_f32 v8, v92, v93
	v_cvt_pk_bf16_f32 v9, v94, v95
	v_cvt_pk_bf16_f32 v10, v88, v89
	v_cvt_pk_bf16_f32 v11, v90, v91
	s_waitcnt vmcnt(1)
	v_cvt_pk_bf16_f32 v12, v96, v97
	v_cvt_pk_bf16_f32 v13, v98, v99
	s_waitcnt vmcnt(0)
	v_cvt_pk_bf16_f32 v14, v100, v101
	v_cvt_pk_bf16_f32 v15, v102, v103
	global_store_dwordx4 v[66:67], v[4:7], off
	global_store_dwordx4 v[104:105], v[0:3], off
	global_store_dwordx4 v[106:107], v[8:11], off
	global_store_dwordx4 v[108:109], v[12:15], off

.Lta_done:
	s_cmp_lt_u32 s2, 0x128
	s_cbranch_scc1 .Lcvt_done
	s_cmp_ge_u32 s2, 0x1e0
	s_cbranch_scc1 .Lcvt_done
	s_load_dwordx2 s[30:31], s[0:1], 0x18
	s_load_dwordx2 s[32:33], s[0:1], 0x20
	s_load_dwordx2 s[34:35], s[0:1], 0x28
	s_load_dwordx2 s[36:37], s[0:1], 0x30
	s_load_dwordx2 s[38:39], s[0:1], 0xe8
	v_lshlrev_b32_e32 v0, 5, v204
	v_lshlrev_b32_e32 v1, 4, v204
	v_add_u32_e32 v2, 0x0, v0
	v_add_u32_e32 v6, 0x0, v1
	v_add_u32_e32 v3, 0x2000, v0
	v_add_u32_e32 v7, 0x1000, v1
	v_add_u32_e32 v4, 0x4000, v0
	v_add_u32_e32 v8, 0x2000, v1
	v_add_u32_e32 v5, 0x6000, v0
	v_add_u32_e32 v9, 0x3000, v1
	s_sub_u32 s4, s2, 0x128
	s_waitcnt lgkmcnt(0)
	s_mov_b32 s5, s4
.Lcvt_c1_m0:
	s_cmpk_lt_u32 s5, 0x400
	s_cbranch_scc1 .Lcvt_c1_d0
	s_sub_u32 s5, s5, 0x400
.Lcvt_c1_m1:
	s_cmpk_lt_u32 s5, 0x400
	s_cbranch_scc1 .Lcvt_c1_d1
	s_sub_u32 s5, s5, 0x400
.Lcvt_c1_m2:
	s_cmpk_lt_u32 s5, 0x80
	s_cbranch_scc1 .Lcvt_c1_d2
	s_sub_u32 s5, s5, 0x80

.Lcvt_c1_d0:
	s_mov_b64 s[18:19], s[30:31]
	s_mov_b32 s20, 0x19f08000
	s_branch .Lcvt_c1_e
.Lcvt_c1_d1:
	s_mov_b64 s[18:19], s[32:33]
	s_mov_b32 s20, 0x1b008000
	s_branch .Lcvt_c1_e
.Lcvt_c1_d2:
	s_mov_b64 s[18:19], s[34:35]
	s_mov_b32 s20, 0x1c708000
	s_branch .Lcvt_c1_e
.Lcvt_c1_d3:
	s_mov_b64 s[18:19], s[36:37]
	s_mov_b32 s20, 0x1c908000
	s_branch .Lcvt_c1_e
.Lcvt_c1_d4:
	s_mov_b64 s[18:19], s[38:39]
	s_mov_b32 s20, 0x19e88000
.Lcvt_c1_e:
	s_lshr_b32 s6, s5, 7
	s_and_b32 s7, s5, 127
	s_lshl_b32 s8, s6, 22
	s_lshl_b32 s9, s7, 15
	s_add_u32 s8, s8, s9
	s_add_u32 s10, s18, s8
	s_addc_u32 s11, s19, 0
	s_mul_i32 s8, s6, 0x220000
	s_lshl_b32 s9, s7, 14
	s_add_u32 s8, s8, s9
	s_add_u32 s8, s8, s20
	s_add_u32 s14, s94, s8
	s_addc_u32 s15, s95, 0
	global_load_dwordx4 v[16:19], v2, s[10:11]
	global_load_dwordx4 v[20:23], v2, s[10:11] offset:16
	global_load_dwordx4 v[24:27], v3, s[10:11]
	global_load_dwordx4 v[28:31], v3, s[10:11] offset:16
	global_load_dwordx4 v[32:35], v4, s[10:11]
	global_load_dwordx4 v[36:39], v4, s[10:11] offset:16
	global_load_dwordx4 v[40:43], v5, s[10:11]
	global_load_dwordx4 v[44:47], v5, s[10:11] offset:16
.Lcvt_loop:
	s_add_u32 s12, s4, 184
	s_cmpk_lt_u32 s12, 0x920
	s_cselect_b32 s13, s12, s4
	s_mov_b32 s5, s13
.Lcvt_c2_m0:
	s_cmpk_lt_u32 s5, 0x400
	s_cbranch_scc1 .Lcvt_c2_d0
	s_sub_u32 s5, s5, 0x400
.Lcvt_c2_m1:
	s_cmpk_lt_u32 s5, 0x400
	s_cbranch_scc1 .Lcvt_c2_d1
	s_sub_u32 s5, s5, 0x400

.Lcvt_c2_e:
	s_lshr_b32 s6, s5, 7
	s_and_b32 s7, s5, 127
	s_lshl_b32 s8, s6, 22
	s_lshl_b32 s9, s7, 15
	s_add_u32 s8, s8, s9
	s_add_u32 s10, s18, s8
	s_addc_u32 s11, s19, 0
	s_mul_i32 s8, s6, 0x220000
	s_lshl_b32 s9, s7, 14
	s_add_u32 s8, s8, s9
	s_add_u32 s8, s8, s20
	s_add_u32 s16, s94, s8
	s_addc_u32 s17, s95, 0
	global_load_dwordx4 v[48:51], v2, s[10:11]
	global_load_dwordx4 v[52:55], v2, s[10:11] offset:16
	global_load_dwordx4 v[56:59], v3, s[10:11]
	global_load_dwordx4 v[60:63], v3, s[10:11] offset:16
	global_load_dwordx4 v[64:67], v4, s[10:11]
	global_load_dwordx4 v[68:71], v4, s[10:11] offset:16
	global_load_dwordx4 v[72:75], v5, s[10:11]
	global_load_dwordx4 v[76:79], v5, s[10:11] offset:16
	s_waitcnt vmcnt(8)
	v_cvt_pk_bf16_f32 v80, v16, v17
	v_cvt_pk_bf16_f32 v81, v18, v19
	v_cvt_pk_bf16_f32 v82, v20, v21
	v_cvt_pk_bf16_f32 v83, v22, v23
	v_cvt_pk_bf16_f32 v84, v24, v25
	v_cvt_pk_bf16_f32 v85, v26, v27
	v_cvt_pk_bf16_f32 v86, v28, v29
	v_cvt_pk_bf16_f32 v87, v30, v31
	v_cvt_pk_bf16_f32 v88, v32, v33
	v_cvt_pk_bf16_f32 v89, v34, v35
	v_cvt_pk_bf16_f32 v90, v36, v37
	v_cvt_pk_bf16_f32 v91, v38, v39
	v_cvt_pk_bf16_f32 v92, v40, v41
	v_cvt_pk_bf16_f32 v93, v42, v43
	v_cvt_pk_bf16_f32 v94, v44, v45
	v_cvt_pk_bf16_f32 v95, v46, v47
	global_store_dwordx4 v6, v[80:83], s[14:15]
	global_store_dwordx4 v7, v[84:87], s[14:15]
	global_store_dwordx4 v8, v[88:91], s[14:15]
	global_store_dwordx4 v9, v[92:95], s[14:15]
	s_mov_b32 s4, s12
	s_cmpk_lt_u32 s4, 0x920
	s_cbranch_scc0 .Lcvt_drain
	s_add_u32 s12, s4, 184
	s_cmpk_lt_u32 s12, 0x920
	s_cselect_b32 s13, s12, s4
	s_mov_b32 s5, s13
.Lcvt_c3_m0:
	s_cmpk_lt_u32 s5, 0x400
	s_cbranch_scc1 .Lcvt_c3_d0
	s_sub_u32 s5, s5, 0x400
.Lcvt_c3_m1:
	s_cmpk_lt_u32 s5, 0x400
	s_cbranch_scc1 .Lcvt_c3_d1
	s_sub_u32 s5, s5, 0x400

.Lcvt_c3_e:
	s_lshr_b32 s6, s5, 7
	s_and_b32 s7, s5, 127
	s_lshl_b32 s8, s6, 22
	s_lshl_b32 s9, s7, 15
	s_add_u32 s8, s8, s9
	s_add_u32 s10, s18, s8
	s_addc_u32 s11, s19, 0
	s_mul_i32 s8, s6, 0x220000
	s_lshl_b32 s9, s7, 14
	s_add_u32 s8, s8, s9
	s_add_u32 s8, s8, s20
	s_add_u32 s14, s94, s8
	s_addc_u32 s15, s95, 0
	global_load_dwordx4 v[16:19], v2, s[10:11]
	global_load_dwordx4 v[20:23], v2, s[10:11] offset:16
	global_load_dwordx4 v[24:27], v3, s[10:11]
	global_load_dwordx4 v[28:31], v3, s[10:11] offset:16
	global_load_dwordx4 v[32:35], v4, s[10:11]
	global_load_dwordx4 v[36:39], v4, s[10:11] offset:16
	global_load_dwordx4 v[40:43], v5, s[10:11]
	global_load_dwordx4 v[44:47], v5, s[10:11] offset:16
	s_waitcnt vmcnt(8)
	v_cvt_pk_bf16_f32 v80, v48, v49
	v_cvt_pk_bf16_f32 v81, v50, v51
	v_cvt_pk_bf16_f32 v82, v52, v53
	v_cvt_pk_bf16_f32 v83, v54, v55
	v_cvt_pk_bf16_f32 v84, v56, v57
	v_cvt_pk_bf16_f32 v85, v58, v59
	v_cvt_pk_bf16_f32 v86, v60, v61
	v_cvt_pk_bf16_f32 v87, v62, v63
	v_cvt_pk_bf16_f32 v88, v64, v65
	v_cvt_pk_bf16_f32 v89, v66, v67
	v_cvt_pk_bf16_f32 v90, v68, v69
	v_cvt_pk_bf16_f32 v91, v70, v71
	v_cvt_pk_bf16_f32 v92, v72, v73
	v_cvt_pk_bf16_f32 v93, v74, v75
	v_cvt_pk_bf16_f32 v94, v76, v77
	v_cvt_pk_bf16_f32 v95, v78, v79
	global_store_dwordx4 v6, v[80:83], s[16:17]
	global_store_dwordx4 v7, v[84:87], s[16:17]
	global_store_dwordx4 v8, v[88:91], s[16:17]
	global_store_dwordx4 v9, v[92:95], s[16:17]
	s_mov_b32 s4, s12
	s_cmpk_lt_u32 s4, 0x920
	s_cbranch_scc0 .Lcvt_drain
	s_branch .Lcvt_loop
